# unit heads of P1, P8 (now rotated), P3, P4, P10 moved behind the leading LDS reads of the peeled first load section
# baseline (speedup 1.0000x reference)
.LBB0_767:
	ds_read_b128 v[38:41], v231
	ds_read_b128 v[42:45], v231 offset:1024
	ds_read_b128 v[54:57], v231 offset:2048
	ds_read_b128 v[58:61], v231 offset:3072
	ds_read_b128 v[126:129], v232
	ds_read_b128 v[146:149], v232 offset:1024
	ds_read_b128 v[166:169], v232 offset:2048
	ds_read_b128 v[170:173], v232 offset:3072
	s_add_i32 s71, s71, 1
	s_mul_i32 s0, s71, s82
	s_mul_hi_u32 s1, s71, s3
	s_add_i32 s1, s1, s0
	s_mul_i32 s0, s71, s3
	s_add_u32 s52, s0, s94
	s_addc_u32 s53, s1, s83
	v_cmp_gt_i64_e32 vcc, s[52:53], v[192:193]
	v_cmp_lt_i64_e64 s[4:5], s[52:53], v[190:191]
	s_cbranch_vccnz .LBB0_773
	s_ashr_i32 s0, s52, 31
	s_lshr_b32 s0, s0, 29
	s_add_i32 s0, s52, s0
	s_and_b32 s1, s0, -8
	s_sub_i32 s1, s52, s1
	s_cmp_gt_i32 s1, -1
	s_mov_b64 s[48:49], -1
	s_cbranch_scc0 .LBB0_770
	s_lshl_b32 s2, s1, 6
	s_mov_b64 s[48:49], 0

.LBB0_773:
	s_ashr_i32 s51, s50, 31
	s_lshl_b64 s[0:1], s[50:51], 19
	v_readlane_b32 s12, v255, 8
	v_readlane_b32 s13, v255, 9
	s_add_u32 s52, s12, s0
	s_addc_u32 s53, s13, s1
	s_and_b64 s[0:1], s[4:5], exec
	s_cselect_b32 s0, s53, s11
	s_cselect_b32 s1, s52, s10
	s_ashr_i32 s49, s48, 31
	s_lshl_b64 s[12:13], s[48:49], 19
	s_add_u32 s54, s64, s12
	s_addc_u32 s55, s65, s13
	s_and_b64 s[12:13], s[4:5], exec
	s_cselect_b32 s2, s55, s57
	s_cselect_b32 s7, s54, s56
	s_add_u32 s10, s10, 0x40080
	s_addc_u32 s11, s11, 0
	s_add_u32 s9, s56, 0x100
	s_addc_u32 s12, s57, 0
	s_mov_b32 s13, -2
	s_add_u32 s14, s10, 0xfffc0080
	s_addc_u32 s15, s11, -1
	s_cmp_eq_u32 s13, 12
	s_cselect_b32 s59, s0, s15
	s_cselect_b32 s58, s1, s14
	s_cselect_b32 s57, s2, s12
	s_cselect_b32 s56, s7, s9
	s_add_i32 m0, s67, 0xc000
	ds_read_b128 v[174:177], v233
	ds_read_b128 v[194:197], v233 offset:1024
	ds_read_b128 v[198:201], v233 offset:2048
	ds_read_b128 v[202:205], v233 offset:3072
	ds_read_b128 v[206:209], v233 offset:4096
	ds_read_b128 v[210:213], v233 offset:5120
	ds_read_b128 v[214:217], v233 offset:6144
	ds_read_b128 v[218:221], v233 offset:7168
	global_load_lds_dwordx4 v186, s[10:11]
	s_add_i32 m0, s67, 0xe000
	s_nop 0
	global_load_lds_dwordx4 v188, s[10:11]
	s_waitcnt vmcnt(8) lgkmcnt(0)
	s_barrier
	v_mfma_f32_16x16x32_bf16 v[162:165], v[38:41], v[174:177], 0
	v_mfma_f32_16x16x32_bf16 v[158:161], v[54:57], v[174:177], 0
	v_mfma_f32_16x16x32_bf16 v[142:145], v[38:41], v[198:201], 0
	v_mfma_f32_16x16x32_bf16 v[138:141], v[54:57], v[198:201], 0
	v_mfma_f32_16x16x32_bf16 v[122:125], v[38:41], v[206:209], 0
	v_mfma_f32_16x16x32_bf16 v[118:121], v[54:57], v[206:209], 0
	v_mfma_f32_16x16x32_bf16 v[106:109], v[38:41], v[214:217], 0
	v_mfma_f32_16x16x32_bf16 v[102:105], v[54:57], v[214:217], 0
	v_mfma_f32_16x16x32_bf16 v[162:165], v[42:45], v[194:197], v[162:165]
	v_mfma_f32_16x16x32_bf16 v[158:161], v[58:61], v[194:197], v[158:161]
	v_mfma_f32_16x16x32_bf16 v[142:145], v[42:45], v[202:205], v[142:145]
	v_mfma_f32_16x16x32_bf16 v[138:141], v[58:61], v[202:205], v[138:141]
	v_mfma_f32_16x16x32_bf16 v[122:125], v[42:45], v[210:213], v[122:125]
	v_mfma_f32_16x16x32_bf16 v[118:121], v[58:61], v[210:213], v[118:121]
	v_mfma_f32_16x16x32_bf16 v[106:109], v[42:45], v[218:221], v[106:109]
	v_mfma_f32_16x16x32_bf16 v[102:105], v[58:61], v[218:221], v[102:105]
	v_mfma_f32_16x16x32_bf16 v[154:157], v[126:129], v[174:177], 0
	v_mfma_f32_16x16x32_bf16 v[150:153], v[166:169], v[174:177], 0
	v_mfma_f32_16x16x32_bf16 v[134:137], v[126:129], v[198:201], 0
	v_mfma_f32_16x16x32_bf16 v[130:133], v[166:169], v[198:201], 0
	v_mfma_f32_16x16x32_bf16 v[114:117], v[126:129], v[206:209], 0
	v_mfma_f32_16x16x32_bf16 v[110:113], v[166:169], v[206:209], 0
	v_mfma_f32_16x16x32_bf16 v[98:101], v[126:129], v[214:217], 0
	v_mfma_f32_16x16x32_bf16 v[94:97], v[166:169], v[214:217], 0
	v_mfma_f32_16x16x32_bf16 v[154:157], v[146:149], v[194:197], v[154:157]
	v_mfma_f32_16x16x32_bf16 v[150:153], v[170:173], v[194:197], v[150:153]
	v_mfma_f32_16x16x32_bf16 v[134:137], v[146:149], v[202:205], v[134:137]
	v_mfma_f32_16x16x32_bf16 v[130:133], v[170:173], v[202:205], v[130:133]
	v_mfma_f32_16x16x32_bf16 v[114:117], v[146:149], v[210:213], v[114:117]
	v_mfma_f32_16x16x32_bf16 v[110:113], v[170:173], v[210:213], v[110:113]
	v_mfma_f32_16x16x32_bf16 v[98:101], v[146:149], v[218:221], v[98:101]
	v_mfma_f32_16x16x32_bf16 v[94:97], v[170:173], v[218:221], v[94:97]
	s_barrier
	s_add_i32 s14, s84, s66
	s_add_u32 s98, s56, s20
	s_addc_u32 s99, s57, s21
	s_mov_b32 m0, s14
	ds_read_b128 v[174:177], v233 offset:16384
	ds_read_b128 v[194:197], v233 offset:17408
	ds_read_b128 v[198:201], v233 offset:18432
	ds_read_b128 v[202:205], v233 offset:19456
	ds_read_b128 v[206:209], v233 offset:20480
	ds_read_b128 v[210:213], v233 offset:21504
	ds_read_b128 v[214:217], v233 offset:22528
	ds_read_b128 v[218:221], v233 offset:23552
	global_load_lds_dwordx4 v180, s[56:57]
	s_add_i32 m0, s14, 0x2000
	s_add_u32 s14, s56, 0x40000
	s_addc_u32 s15, s57, 0
	s_add_i32 s33, s85, s66
	global_load_lds_dwordx4 v184, s[56:57]
	s_mov_b32 m0, s33
	s_add_u32 s100, s58, s20
	s_addc_u32 s101, s59, s21
	global_load_lds_dwordx4 v180, s[14:15]
	s_add_i32 m0, s33, 0x2000
	s_nop 0
	global_load_lds_dwordx4 v184, s[14:15]
	s_mov_b32 m0, s67
	s_nop 0
	global_load_lds_dwordx4 v178, s[58:59]
	s_mov_b32 m0, s68
	s_nop 0
	global_load_lds_dwordx4 v182, s[58:59]
	s_waitcnt vmcnt(8) lgkmcnt(0)
	s_barrier
	v_mfma_f32_16x16x32_bf16 v[90:93], v[38:41], v[174:177], 0
	v_mfma_f32_16x16x32_bf16 v[86:89], v[54:57], v[174:177], 0
	v_mfma_f32_16x16x32_bf16 v[74:77], v[38:41], v[198:201], 0
	v_mfma_f32_16x16x32_bf16 v[70:73], v[54:57], v[198:201], 0
	v_mfma_f32_16x16x32_bf16 v[50:53], v[38:41], v[206:209], 0
	v_mfma_f32_16x16x32_bf16 v[46:49], v[54:57], v[206:209], 0
	v_mfma_f32_16x16x32_bf16 v[26:29], v[38:41], v[214:217], 0
	v_mfma_f32_16x16x32_bf16 v[22:25], v[54:57], v[214:217], 0
	v_mfma_f32_16x16x32_bf16 v[90:93], v[42:45], v[194:197], v[90:93]
	v_mfma_f32_16x16x32_bf16 v[86:89], v[58:61], v[194:197], v[86:89]
	v_mfma_f32_16x16x32_bf16 v[74:77], v[42:45], v[202:205], v[74:77]
	v_mfma_f32_16x16x32_bf16 v[70:73], v[58:61], v[202:205], v[70:73]
	v_mfma_f32_16x16x32_bf16 v[50:53], v[42:45], v[210:213], v[50:53]
	v_mfma_f32_16x16x32_bf16 v[46:49], v[58:61], v[210:213], v[46:49]
	v_mfma_f32_16x16x32_bf16 v[26:29], v[42:45], v[218:221], v[26:29]
	v_mfma_f32_16x16x32_bf16 v[22:25], v[58:61], v[218:221], v[22:25]
	v_mfma_f32_16x16x32_bf16 v[34:37], v[126:129], v[206:209], 0
	v_mfma_f32_16x16x32_bf16 v[30:33], v[166:169], v[206:209], 0
	v_mfma_f32_16x16x32_bf16 v[18:21], v[126:129], v[214:217], 0
	v_mfma_f32_16x16x32_bf16 v[12:15], v[166:169], v[214:217], 0
	v_mfma_f32_16x16x32_bf16 v[38:41], v[126:129], v[174:177], 0
	v_mfma_f32_16x16x32_bf16 v[42:45], v[166:169], v[174:177], 0
	v_mfma_f32_16x16x32_bf16 v[54:57], v[126:129], v[198:201], 0
	v_mfma_f32_16x16x32_bf16 v[58:61], v[166:169], v[198:201], 0
	v_mfma_f32_16x16x32_bf16 v[34:37], v[146:149], v[210:213], v[34:37]
	v_mfma_f32_16x16x32_bf16 v[30:33], v[170:173], v[210:213], v[30:33]
	v_mfma_f32_16x16x32_bf16 v[18:21], v[146:149], v[218:221], v[18:21]
	v_mfma_f32_16x16x32_bf16 v[12:15], v[170:173], v[218:221], v[12:15]
	v_mfma_f32_16x16x32_bf16 v[38:41], v[146:149], v[194:197], v[38:41]
	v_mfma_f32_16x16x32_bf16 v[42:45], v[170:173], v[194:197], v[42:45]
	v_mfma_f32_16x16x32_bf16 v[54:57], v[146:149], v[202:205], v[54:57]
	v_mfma_f32_16x16x32_bf16 v[58:61], v[170:173], v[202:205], v[58:61]
	s_barrier
	s_branch .Lpeel3_p3

.LBB0_1033:
	ds_read_b128 v[26:29], v214
	ds_read_b128 v[30:33], v214 offset:1024
	ds_read_b128 v[34:37], v214 offset:2048
	ds_read_b128 v[38:41], v214 offset:3072
	ds_read_b128 v[122:125], v215
	ds_read_b128 v[142:145], v215 offset:1024
	ds_read_b128 v[162:165], v215 offset:2048
	ds_read_b128 v[166:169], v215 offset:3072
	s_add_i32 s71, s71, 1
	s_mul_i32 s1, s71, s83
	s_mul_hi_u32 s2, s71, s3
	s_add_i32 s2, s2, s1
	s_mul_i32 s1, s71, s3
	s_add_u32 s4, s1, s94
	s_addc_u32 s5, s2, s84
	v_cmp_gt_i64_e32 vcc, s[4:5], v[196:197]
	v_cmp_lt_i64_e64 s[6:7], s[4:5], v[194:195]
	s_cbranch_vccnz .LBB0_1035
	s_ashr_i32 s1, s4, 31
	s_lshr_b32 s1, s1, 29
	s_add_i32 s1, s4, s1
	s_ashr_i32 s2, s1, 3
	s_and_b32 s1, s1, -8
	s_sub_i32 s1, s4, s1
	s_cmp_lt_i32 s1, 0
	s_cselect_b32 s4, 57, 56
	s_mul_i32 s1, s4, s1
	s_add_i32 s1, s1, s2
	s_mul_hi_i32 s2, s1, 0x92492493
	s_add_i32 s2, s2, s1
	s_lshr_b32 s4, s2, 31
	s_ashr_i32 s2, s2, 5
	s_add_i32 s2, s2, s4
	s_lshl_b32 s4, s2, 3
	s_sub_i32 s5, 64, s4
	s_min_i32 s5, s5, 8
	s_mul_i32 s2, s2, 56
	s_sub_i32 s1, s1, s2
	s_lshr_b32 s30, s1, 3
	s_and_b32 s1, s1, 7
	s_add_i32 s88, s1, s4

.LBB0_1037:
	s_ashr_i32 s31, s30, 31
	s_lshl_b64 s[8:9], s[30:31], 17
	s_add_u32 s48, s62, s8
	s_addc_u32 s49, s63, s9
	s_and_b64 s[6:7], s[6:7], exec
	s_cselect_b32 s1, s49, s53
	s_cselect_b32 s2, s48, s52
	s_cmp_lt_i32 s50, 3
	s_cselect_b64 s[8:9], -1, 0
	s_and_b64 s[6:7], s[8:9], exec
	s_cselect_b32 s12, 4, 2
	s_add_i32 s13, s12, -2
	s_add_u32 s6, s54, 0x30080
	s_addc_u32 s7, s55, 0
	s_add_u32 s14, s52, 0x100
	s_addc_u32 s15, s53, 0
	s_mov_b32 s31, 0
	s_add_i32 s33, s31, 2
	s_add_u32 s40, s6, 0xfffd0080
	s_addc_u32 s41, s7, -1
	s_cmp_eq_u32 s13, s31
	s_cselect_b32 s55, s47, s41
	s_cselect_b32 s54, s46, s40
	s_cselect_b32 s53, s1, s15
	s_cselect_b32 s52, s2, s14
	s_add_i32 m0, s66, 0xc000
	ds_read_b128 v[170:173], v216
	ds_read_b128 v[174:177], v216 offset:1024
	ds_read_b128 v[178:181], v216 offset:2048
	ds_read_b128 v[198:201], v216 offset:3072
	ds_read_b128 v[202:205], v216 offset:4096
	ds_read_b128 v[206:209], v216 offset:5120
	ds_read_b128 v[220:223], v216 offset:6144
	ds_read_b128 v[228:231], v216 offset:7168
	global_load_lds_dwordx4 v190, s[6:7]
	s_add_i32 m0, s66, 0xe000
	s_nop 0
	global_load_lds_dwordx4 v192, s[6:7]
	s_waitcnt vmcnt(8) lgkmcnt(0)
	s_barrier
	v_mfma_f32_16x16x32_bf16 v[158:161], v[26:29], v[170:173], 0
	v_mfma_f32_16x16x32_bf16 v[154:157], v[34:37], v[170:173], 0
	v_mfma_f32_16x16x32_bf16 v[138:141], v[26:29], v[178:181], 0
	v_mfma_f32_16x16x32_bf16 v[134:137], v[34:37], v[178:181], 0
	v_mfma_f32_16x16x32_bf16 v[118:121], v[26:29], v[202:205], 0
	v_mfma_f32_16x16x32_bf16 v[114:117], v[34:37], v[202:205], 0
	v_mfma_f32_16x16x32_bf16 v[102:105], v[26:29], v[220:223], 0
	v_mfma_f32_16x16x32_bf16 v[98:101], v[34:37], v[220:223], 0
	v_mfma_f32_16x16x32_bf16 v[158:161], v[30:33], v[174:177], v[158:161]
	v_mfma_f32_16x16x32_bf16 v[154:157], v[38:41], v[174:177], v[154:157]
	v_mfma_f32_16x16x32_bf16 v[138:141], v[30:33], v[198:201], v[138:141]
	v_mfma_f32_16x16x32_bf16 v[134:137], v[38:41], v[198:201], v[134:137]
	v_mfma_f32_16x16x32_bf16 v[118:121], v[30:33], v[206:209], v[118:121]
	v_mfma_f32_16x16x32_bf16 v[114:117], v[38:41], v[206:209], v[114:117]
	v_mfma_f32_16x16x32_bf16 v[102:105], v[30:33], v[228:231], v[102:105]
	v_mfma_f32_16x16x32_bf16 v[98:101], v[38:41], v[228:231], v[98:101]
	v_mfma_f32_16x16x32_bf16 v[150:153], v[122:125], v[170:173], 0
	v_mfma_f32_16x16x32_bf16 v[146:149], v[162:165], v[170:173], 0
	v_mfma_f32_16x16x32_bf16 v[130:133], v[122:125], v[178:181], 0
	v_mfma_f32_16x16x32_bf16 v[126:129], v[162:165], v[178:181], 0
	v_mfma_f32_16x16x32_bf16 v[110:113], v[122:125], v[202:205], 0
	v_mfma_f32_16x16x32_bf16 v[106:109], v[162:165], v[202:205], 0
	v_mfma_f32_16x16x32_bf16 v[94:97], v[122:125], v[220:223], 0
	v_mfma_f32_16x16x32_bf16 v[90:93], v[162:165], v[220:223], 0
	v_mfma_f32_16x16x32_bf16 v[150:153], v[142:145], v[174:177], v[150:153]
	v_mfma_f32_16x16x32_bf16 v[146:149], v[166:169], v[174:177], v[146:149]
	v_mfma_f32_16x16x32_bf16 v[130:133], v[142:145], v[198:201], v[130:133]
	v_mfma_f32_16x16x32_bf16 v[126:129], v[166:169], v[198:201], v[126:129]
	v_mfma_f32_16x16x32_bf16 v[110:113], v[142:145], v[206:209], v[110:113]
	v_mfma_f32_16x16x32_bf16 v[106:109], v[166:169], v[206:209], v[106:109]
	v_mfma_f32_16x16x32_bf16 v[94:97], v[142:145], v[228:231], v[94:97]
	v_mfma_f32_16x16x32_bf16 v[90:93], v[166:169], v[228:231], v[90:93]
	s_barrier
	s_add_i32 s31, s85, s64
	s_add_u32 s98, s52, s18
	s_addc_u32 s99, s53, s19
	s_mov_b32 m0, s31
	ds_read_b128 v[170:173], v216 offset:16384
	ds_read_b128 v[174:177], v216 offset:17408
	ds_read_b128 v[178:181], v216 offset:18432
	ds_read_b128 v[198:201], v216 offset:19456
	ds_read_b128 v[202:205], v216 offset:20480
	ds_read_b128 v[206:209], v216 offset:21504
	ds_read_b128 v[220:223], v216 offset:22528
	ds_read_b128 v[228:231], v216 offset:23552
	global_load_lds_dwordx4 v184, s[52:53]
	s_add_i32 m0, s31, 0x2000
	s_add_u32 s40, s52, 0x10000
	s_addc_u32 s41, s53, 0
	s_add_i32 s31, s86, s64
	global_load_lds_dwordx4 v188, s[52:53]
	s_mov_b32 m0, s31
	s_add_u32 s100, s54, s18
	s_addc_u32 s101, s55, s19
	global_load_lds_dwordx4 v184, s[40:41]
	s_add_i32 m0, s31, 0x2000
	s_nop 0
	global_load_lds_dwordx4 v188, s[40:41]
	s_mov_b32 m0, s66
	s_nop 0
	global_load_lds_dwordx4 v182, s[54:55]
	s_mov_b32 m0, s67
	s_nop 0
	global_load_lds_dwordx4 v186, s[54:55]
	s_waitcnt vmcnt(8) lgkmcnt(0)
	s_barrier
	v_mfma_f32_16x16x32_bf16 v[86:89], v[26:29], v[170:173], 0
	v_mfma_f32_16x16x32_bf16 v[82:85], v[34:37], v[170:173], 0
	v_mfma_f32_16x16x32_bf16 v[70:73], v[26:29], v[178:181], 0
	v_mfma_f32_16x16x32_bf16 v[66:69], v[34:37], v[178:181], 0
	v_mfma_f32_16x16x32_bf16 v[54:57], v[26:29], v[202:205], 0
	v_mfma_f32_16x16x32_bf16 v[50:53], v[34:37], v[202:205], 0
	v_mfma_f32_16x16x32_bf16 v[22:25], v[26:29], v[220:223], 0
	v_mfma_f32_16x16x32_bf16 v[18:21], v[34:37], v[220:223], 0
	v_mfma_f32_16x16x32_bf16 v[86:89], v[30:33], v[174:177], v[86:89]
	v_mfma_f32_16x16x32_bf16 v[82:85], v[38:41], v[174:177], v[82:85]
	v_mfma_f32_16x16x32_bf16 v[70:73], v[30:33], v[198:201], v[70:73]
	v_mfma_f32_16x16x32_bf16 v[66:69], v[38:41], v[198:201], v[66:69]
	v_mfma_f32_16x16x32_bf16 v[54:57], v[30:33], v[206:209], v[54:57]
	v_mfma_f32_16x16x32_bf16 v[50:53], v[38:41], v[206:209], v[50:53]
	v_mfma_f32_16x16x32_bf16 v[22:25], v[30:33], v[228:231], v[22:25]
	v_mfma_f32_16x16x32_bf16 v[18:21], v[38:41], v[228:231], v[18:21]
	v_mfma_f32_16x16x32_bf16 v[46:49], v[122:125], v[202:205], 0
	v_mfma_f32_16x16x32_bf16 v[42:45], v[162:165], v[202:205], 0
	v_mfma_f32_16x16x32_bf16 v[14:17], v[122:125], v[220:223], 0
	v_mfma_f32_16x16x32_bf16 v[8:11], v[162:165], v[220:223], 0
	v_mfma_f32_16x16x32_bf16 v[26:29], v[122:125], v[170:173], 0
	v_mfma_f32_16x16x32_bf16 v[30:33], v[162:165], v[170:173], 0
	v_mfma_f32_16x16x32_bf16 v[34:37], v[122:125], v[178:181], 0
	v_mfma_f32_16x16x32_bf16 v[38:41], v[162:165], v[178:181], 0
	v_mfma_f32_16x16x32_bf16 v[46:49], v[142:145], v[206:209], v[46:49]
	v_mfma_f32_16x16x32_bf16 v[42:45], v[166:169], v[206:209], v[42:45]
	v_mfma_f32_16x16x32_bf16 v[14:17], v[142:145], v[228:231], v[14:17]
	v_mfma_f32_16x16x32_bf16 v[8:11], v[166:169], v[228:231], v[8:11]
	v_mfma_f32_16x16x32_bf16 v[26:29], v[142:145], v[174:177], v[26:29]
	v_mfma_f32_16x16x32_bf16 v[30:33], v[166:169], v[174:177], v[30:33]
	v_mfma_f32_16x16x32_bf16 v[34:37], v[142:145], v[198:201], v[34:37]
	v_mfma_f32_16x16x32_bf16 v[38:41], v[166:169], v[198:201], v[38:41]
	s_barrier
	s_branch .Lpeel4_p3

.LBB0_1761:
	v_add_u32_e32 v146, s53, v217
	v_add_u32_e32 v162, s54, v217
	ds_read_b128 v[134:137], v146
	ds_read_b128 v[138:141], v146 offset:1024
	ds_read_b128 v[142:145], v146 offset:2048
	ds_read_b128 v[146:149], v146 offset:3072
	ds_read_b128 v[150:153], v162
	ds_read_b128 v[154:157], v162 offset:1024
	ds_read_b128 v[158:161], v162 offset:2048
	ds_read_b128 v[162:165], v162 offset:3072
	ds_read_b128 v[166:169], v220
	ds_read_b128 v[170:173], v220 offset:1024
	ds_read_b128 v[174:177], v220 offset:2048
	ds_read_b128 v[178:181], v220 offset:3072
	ds_read_b128 v[182:185], v220 offset:4096
	ds_read_b128 v[186:189], v220 offset:5120
	ds_read_b128 v[190:193], v220 offset:6144
	ds_read_b128 v[194:197], v220 offset:7168
	s_add_i32 s44, s44, 1
	s_mul_i32 s6, s44, s15
	s_mul_hi_u32 s7, s44, s3
	s_add_i32 s7, s7, s6
	s_mul_i32 s6, s44, s3
	s_add_u32 s24, s6, s94
	s_addc_u32 s25, s7, s13
	v_cmp_gt_i64_e32 vcc, s[24:25], v[212:213]
	v_cmp_lt_i64_e64 s[6:7], s[24:25], v[210:211]
	s_cbranch_vccnz .LBB0_1763
	s_ashr_i32 s20, s24, 31
	s_lshr_b32 s20, s20, 29
	s_add_i32 s20, s24, s20
	s_ashr_i32 s21, s20, 3
	s_and_b32 s20, s20, -8
	s_sub_i32 s20, s24, s20
	s_cmp_lt_i32 s20, 0
	s_cselect_b32 s22, s33, 0xb0
	s_mul_i32 s20, s22, s20
	s_add_i32 s20, s20, s21
	s_mul_hi_i32 s21, s20, 0x2e8ba2e9
	s_lshr_b32 s22, s21, 31
	s_ashr_i32 s21, s21, 5
	s_add_i32 s21, s21, s22
	s_lshl_b32 s22, s21, 3
	s_sub_i32 s23, 64, s22
	s_min_i32 s23, s23, 8
	s_mulk_i32 s21, 0xb0
	s_sub_i32 s21, s20, s21
	s_lshr_b32 s20, s21, 3
	s_and_b32 s21, s21, 7
	s_add_i32 s22, s21, s22
.LBB0_1763:
	s_ashr_i32 s23, s22, 31
	s_lshl_b64 s[24:25], s[22:23], 19
	s_add_u32 s24, s68, s24
	s_addc_u32 s25, s69, s25
	s_and_b64 s[26:27], s[6:7], exec
	s_cselect_b32 s23, s25, s47
	s_cselect_b32 s56, s24, s46
	s_ashr_i32 s21, s20, 31
	s_lshl_b64 s[26:27], s[20:21], 19
	s_add_u32 s26, s0, s26
	s_addc_u32 s27, s1, s27
	s_and_b64 s[48:49], s[6:7], exec
	s_cselect_b32 s57, s27, s31
	s_cselect_b32 s58, s26, s30
	s_lshl_b32 s21, s28, 8
	v_add_u32_e32 v6, s21, v218
	s_add_u32 s28, s46, 0x3ff80
	v_ashrrev_i32_e32 v7, 31, v6
	s_addc_u32 s29, s47, 0
	v_lshl_add_u64 v[214:215], v[6:7], 4, s[8:9]
	s_add_u32 s59, s30, 0
	s_addc_u32 s60, s31, 0
	s_mov_b32 s61, -2
	s_add_u32 s28, s28, 0x100
	s_addc_u32 s29, s29, 0
	s_add_u32 s59, s59, 0x100
	s_addc_u32 s60, s60, 0
	s_cmp_eq_u32 s61, 12
	s_cselect_b64 s[30:31], -1, 0
	s_cbranch_scc0 .Lpeel8_1768
	global_load_dwordx4 v[2:5], v[214:215], off
.Lpeel8_1768:
	s_add_u32 s48, s28, 0xfffc0080
	s_addc_u32 s49, s29, -1
	s_and_b64 s[46:47], s[30:31], exec
	s_cselect_b32 s49, s23, s49
	s_cselect_b32 s48, s56, s48
	s_cselect_b32 s47, s57, s60
	s_cselect_b32 s46, s58, s59
	s_add_i32 m0, s40, 0xc000
	s_nop 0
	global_load_lds_dwordx4 v206, s[28:29]
	s_add_i32 m0, s40, 0xe000
	s_nop 0
	global_load_lds_dwordx4 v208, s[28:29]
	s_waitcnt vmcnt(8) lgkmcnt(0)
	s_barrier
	v_mfma_f32_16x16x32_bf16 v[130:133], v[134:137], v[166:169], 0
	v_mfma_f32_16x16x32_bf16 v[122:125], v[142:145], v[166:169], 0
	v_mfma_f32_16x16x32_bf16 v[114:117], v[134:137], v[174:177], 0
	v_mfma_f32_16x16x32_bf16 v[106:109], v[142:145], v[174:177], 0
	v_mfma_f32_16x16x32_bf16 v[98:101], v[134:137], v[182:185], 0
	v_mfma_f32_16x16x32_bf16 v[90:93], v[142:145], v[182:185], 0
	v_mfma_f32_16x16x32_bf16 v[82:85], v[134:137], v[190:193], 0
	v_mfma_f32_16x16x32_bf16 v[74:77], v[142:145], v[190:193], 0
	v_mfma_f32_16x16x32_bf16 v[130:133], v[138:141], v[170:173], v[130:133]
	v_mfma_f32_16x16x32_bf16 v[122:125], v[146:149], v[170:173], v[122:125]
	v_mfma_f32_16x16x32_bf16 v[114:117], v[138:141], v[178:181], v[114:117]
	v_mfma_f32_16x16x32_bf16 v[106:109], v[146:149], v[178:181], v[106:109]
	v_mfma_f32_16x16x32_bf16 v[98:101], v[138:141], v[186:189], v[98:101]
	v_mfma_f32_16x16x32_bf16 v[90:93], v[146:149], v[186:189], v[90:93]
	v_mfma_f32_16x16x32_bf16 v[82:85], v[138:141], v[194:197], v[82:85]
	v_mfma_f32_16x16x32_bf16 v[74:77], v[146:149], v[194:197], v[74:77]
	v_mfma_f32_16x16x32_bf16 v[126:129], v[150:153], v[166:169], 0
	v_mfma_f32_16x16x32_bf16 v[118:121], v[158:161], v[166:169], 0
	v_mfma_f32_16x16x32_bf16 v[110:113], v[150:153], v[174:177], 0
	v_mfma_f32_16x16x32_bf16 v[102:105], v[158:161], v[174:177], 0
	v_mfma_f32_16x16x32_bf16 v[94:97], v[150:153], v[182:185], 0
	v_mfma_f32_16x16x32_bf16 v[86:89], v[158:161], v[182:185], 0
	v_mfma_f32_16x16x32_bf16 v[78:81], v[150:153], v[190:193], 0
	v_mfma_f32_16x16x32_bf16 v[70:73], v[158:161], v[190:193], 0
	v_mfma_f32_16x16x32_bf16 v[126:129], v[154:157], v[170:173], v[126:129]
	v_mfma_f32_16x16x32_bf16 v[118:121], v[162:165], v[170:173], v[118:121]
	v_mfma_f32_16x16x32_bf16 v[110:113], v[154:157], v[178:181], v[110:113]
	v_mfma_f32_16x16x32_bf16 v[102:105], v[162:165], v[178:181], v[102:105]
	v_mfma_f32_16x16x32_bf16 v[94:97], v[154:157], v[186:189], v[94:97]
	v_mfma_f32_16x16x32_bf16 v[86:89], v[162:165], v[186:189], v[86:89]
	v_mfma_f32_16x16x32_bf16 v[78:81], v[154:157], v[194:197], v[78:81]
	v_mfma_f32_16x16x32_bf16 v[70:73], v[162:165], v[194:197], v[70:73]
	s_barrier
	ds_read_b128 v[166:169], v220 offset:16384
	ds_read_b128 v[170:173], v220 offset:17408
	ds_read_b128 v[174:177], v220 offset:18432
	ds_read_b128 v[178:181], v220 offset:19456
	ds_read_b128 v[182:185], v220 offset:20480
	ds_read_b128 v[186:189], v220 offset:21504
	ds_read_b128 v[190:193], v220 offset:22528
	ds_read_b128 v[194:197], v220 offset:23552
	s_add_i32 s62, s53, s12
	s_add_u32 s98, s46, s16
	s_addc_u32 s99, s47, s17
	s_mov_b32 m0, s62
	s_nop 0
	global_load_lds_dwordx4 v202, s[46:47]
	s_add_i32 m0, s62, 0x2000
	s_add_u32 s62, s46, 0x40000
	s_addc_u32 s63, s47, 0
	s_add_i32 s64, s54, s12
	global_load_lds_dwordx4 v198, s[46:47]
	s_mov_b32 m0, s64
	s_nop 0
	global_load_lds_dwordx4 v202, s[62:63]
	s_add_i32 m0, s64, 0x2000
	s_nop 0
	global_load_lds_dwordx4 v198, s[62:63]
	s_add_u32 s100, s48, s16
	s_addc_u32 s101, s49, s17
	s_mov_b32 m0, s40
	s_nop 0
	global_load_lds_dwordx4 v204, s[48:49]
	s_mov_b32 m0, s41
	s_nop 0
	global_load_lds_dwordx4 v200, s[48:49]
	s_waitcnt vmcnt(8) lgkmcnt(0)
	s_barrier
	v_mfma_f32_16x16x32_bf16 v[66:69], v[134:137], v[166:169], 0
	v_mfma_f32_16x16x32_bf16 v[58:61], v[142:145], v[166:169], 0
	v_mfma_f32_16x16x32_bf16 v[50:53], v[134:137], v[174:177], 0
	v_mfma_f32_16x16x32_bf16 v[42:45], v[142:145], v[174:177], 0
	v_mfma_f32_16x16x32_bf16 v[34:37], v[134:137], v[182:185], 0
	v_mfma_f32_16x16x32_bf16 v[26:29], v[142:145], v[182:185], 0
	v_mfma_f32_16x16x32_bf16 v[18:21], v[134:137], v[190:193], 0
	v_mfma_f32_16x16x32_bf16 v[10:13], v[142:145], v[190:193], 0
	v_mfma_f32_16x16x32_bf16 v[66:69], v[138:141], v[170:173], v[66:69]
	v_mfma_f32_16x16x32_bf16 v[58:61], v[146:149], v[170:173], v[58:61]
	v_mfma_f32_16x16x32_bf16 v[50:53], v[138:141], v[178:181], v[50:53]
	v_mfma_f32_16x16x32_bf16 v[42:45], v[146:149], v[178:181], v[42:45]
	v_mfma_f32_16x16x32_bf16 v[34:37], v[138:141], v[186:189], v[34:37]
	v_mfma_f32_16x16x32_bf16 v[26:29], v[146:149], v[186:189], v[26:29]
	v_mfma_f32_16x16x32_bf16 v[18:21], v[138:141], v[194:197], v[18:21]
	v_mfma_f32_16x16x32_bf16 v[10:13], v[146:149], v[194:197], v[10:13]
	v_mfma_f32_16x16x32_bf16 v[62:65], v[150:153], v[166:169], 0
	v_mfma_f32_16x16x32_bf16 v[54:57], v[158:161], v[166:169], 0
	v_mfma_f32_16x16x32_bf16 v[46:49], v[150:153], v[174:177], 0
	v_mfma_f32_16x16x32_bf16 v[38:41], v[158:161], v[174:177], 0
	v_mfma_f32_16x16x32_bf16 v[30:33], v[150:153], v[182:185], 0
	v_mfma_f32_16x16x32_bf16 v[22:25], v[158:161], v[182:185], 0
	v_mfma_f32_16x16x32_bf16 v[14:17], v[150:153], v[190:193], 0
	v_mfma_f32_16x16x32_bf16 v[6:9], v[158:161], v[190:193], 0
	v_mfma_f32_16x16x32_bf16 v[62:65], v[154:157], v[170:173], v[62:65]
	v_mfma_f32_16x16x32_bf16 v[54:57], v[162:165], v[170:173], v[54:57]
	v_mfma_f32_16x16x32_bf16 v[46:49], v[154:157], v[178:181], v[46:49]
	v_mfma_f32_16x16x32_bf16 v[38:41], v[162:165], v[178:181], v[38:41]
	v_mfma_f32_16x16x32_bf16 v[30:33], v[154:157], v[186:189], v[30:33]
	v_mfma_f32_16x16x32_bf16 v[22:25], v[162:165], v[186:189], v[22:25]
	v_mfma_f32_16x16x32_bf16 v[14:17], v[154:157], v[194:197], v[14:17]
	v_mfma_f32_16x16x32_bf16 v[6:9], v[162:165], v[194:197], v[6:9]
	s_barrier
	s_branch .Lpeel8_p3

.LBB0_1768:
	s_add_u32 s48, s28, 0xfffc0080
	s_addc_u32 s49, s29, -1
	s_and_b64 s[46:47], s[30:31], exec
	s_cselect_b32 s49, s23, s49
	s_cselect_b32 s48, s56, s48
	s_cselect_b32 s47, s57, s60
	s_cselect_b32 s46, s58, s59
	s_add_i32 m0, s40, 0xc000
	s_nop 0
	global_load_lds_dwordx4 v206, s[28:29]
	s_add_i32 m0, s40, 0xe000
	s_nop 0
	global_load_lds_dwordx4 v208, s[28:29]
	s_waitcnt vmcnt(8) lgkmcnt(0)
	s_barrier
	v_mfma_f32_16x16x32_bf16 v[130:133], v[134:137], v[166:169], v[130:133]
	v_mfma_f32_16x16x32_bf16 v[122:125], v[142:145], v[166:169], v[122:125]
	v_mfma_f32_16x16x32_bf16 v[114:117], v[134:137], v[174:177], v[114:117]
	v_mfma_f32_16x16x32_bf16 v[106:109], v[142:145], v[174:177], v[106:109]
	v_mfma_f32_16x16x32_bf16 v[98:101], v[134:137], v[182:185], v[98:101]
	v_mfma_f32_16x16x32_bf16 v[90:93], v[142:145], v[182:185], v[90:93]
	v_mfma_f32_16x16x32_bf16 v[82:85], v[134:137], v[190:193], v[82:85]
	v_mfma_f32_16x16x32_bf16 v[74:77], v[142:145], v[190:193], v[74:77]
	v_mfma_f32_16x16x32_bf16 v[130:133], v[138:141], v[170:173], v[130:133]
	v_mfma_f32_16x16x32_bf16 v[122:125], v[146:149], v[170:173], v[122:125]
	v_mfma_f32_16x16x32_bf16 v[114:117], v[138:141], v[178:181], v[114:117]
	v_mfma_f32_16x16x32_bf16 v[106:109], v[146:149], v[178:181], v[106:109]
	v_mfma_f32_16x16x32_bf16 v[98:101], v[138:141], v[186:189], v[98:101]
	v_mfma_f32_16x16x32_bf16 v[90:93], v[146:149], v[186:189], v[90:93]
	v_mfma_f32_16x16x32_bf16 v[82:85], v[138:141], v[194:197], v[82:85]
	v_mfma_f32_16x16x32_bf16 v[74:77], v[146:149], v[194:197], v[74:77]
	v_mfma_f32_16x16x32_bf16 v[126:129], v[150:153], v[166:169], v[126:129]
	v_mfma_f32_16x16x32_bf16 v[118:121], v[158:161], v[166:169], v[118:121]
	v_mfma_f32_16x16x32_bf16 v[110:113], v[150:153], v[174:177], v[110:113]
	v_mfma_f32_16x16x32_bf16 v[102:105], v[158:161], v[174:177], v[102:105]
	v_mfma_f32_16x16x32_bf16 v[94:97], v[150:153], v[182:185], v[94:97]
	v_mfma_f32_16x16x32_bf16 v[86:89], v[158:161], v[182:185], v[86:89]
	v_mfma_f32_16x16x32_bf16 v[78:81], v[150:153], v[190:193], v[78:81]
	v_mfma_f32_16x16x32_bf16 v[70:73], v[158:161], v[190:193], v[70:73]
	v_mfma_f32_16x16x32_bf16 v[126:129], v[154:157], v[170:173], v[126:129]
	v_mfma_f32_16x16x32_bf16 v[118:121], v[162:165], v[170:173], v[118:121]
	v_mfma_f32_16x16x32_bf16 v[110:113], v[154:157], v[178:181], v[110:113]
	v_mfma_f32_16x16x32_bf16 v[102:105], v[162:165], v[178:181], v[102:105]
	v_mfma_f32_16x16x32_bf16 v[94:97], v[154:157], v[186:189], v[94:97]
	v_mfma_f32_16x16x32_bf16 v[86:89], v[162:165], v[186:189], v[86:89]
	v_mfma_f32_16x16x32_bf16 v[78:81], v[154:157], v[194:197], v[78:81]
	v_mfma_f32_16x16x32_bf16 v[70:73], v[162:165], v[194:197], v[70:73]
	s_barrier
	ds_read_b128 v[166:169], v220 offset:16384
	ds_read_b128 v[170:173], v220 offset:17408
	ds_read_b128 v[174:177], v220 offset:18432
	ds_read_b128 v[178:181], v220 offset:19456
	ds_read_b128 v[182:185], v220 offset:20480
	ds_read_b128 v[186:189], v220 offset:21504
	ds_read_b128 v[190:193], v220 offset:22528
	ds_read_b128 v[194:197], v220 offset:23552
	s_add_i32 s62, s53, s12
	s_add_u32 s98, s46, s16
	s_addc_u32 s99, s47, s17
	s_mov_b32 m0, s62
	s_nop 0
	global_load_lds_dwordx4 v202, s[46:47]
	s_add_i32 m0, s62, 0x2000
	s_add_u32 s62, s46, 0x40000
	s_addc_u32 s63, s47, 0
	s_add_i32 s64, s54, s12
	global_load_lds_dwordx4 v198, s[46:47]
	s_mov_b32 m0, s64
	s_nop 0
	global_load_lds_dwordx4 v202, s[62:63]
	s_add_i32 m0, s64, 0x2000
	s_nop 0
	global_load_lds_dwordx4 v198, s[62:63]
	s_add_u32 s100, s48, s16
	s_addc_u32 s101, s49, s17
	s_mov_b32 m0, s40
	s_nop 0
	global_load_lds_dwordx4 v204, s[48:49]
	s_mov_b32 m0, s41
	s_nop 0
	global_load_lds_dwordx4 v200, s[48:49]
	s_waitcnt vmcnt(8) lgkmcnt(0)
	s_barrier
	v_mfma_f32_16x16x32_bf16 v[66:69], v[134:137], v[166:169], v[66:69]
	v_mfma_f32_16x16x32_bf16 v[58:61], v[142:145], v[166:169], v[58:61]
	v_mfma_f32_16x16x32_bf16 v[50:53], v[134:137], v[174:177], v[50:53]
	v_mfma_f32_16x16x32_bf16 v[42:45], v[142:145], v[174:177], v[42:45]
	v_mfma_f32_16x16x32_bf16 v[34:37], v[134:137], v[182:185], v[34:37]
	v_mfma_f32_16x16x32_bf16 v[26:29], v[142:145], v[182:185], v[26:29]
	v_mfma_f32_16x16x32_bf16 v[18:21], v[134:137], v[190:193], v[18:21]
	v_mfma_f32_16x16x32_bf16 v[10:13], v[142:145], v[190:193], v[10:13]
	v_mfma_f32_16x16x32_bf16 v[66:69], v[138:141], v[170:173], v[66:69]
	v_mfma_f32_16x16x32_bf16 v[58:61], v[146:149], v[170:173], v[58:61]
	v_mfma_f32_16x16x32_bf16 v[50:53], v[138:141], v[178:181], v[50:53]
	v_mfma_f32_16x16x32_bf16 v[42:45], v[146:149], v[178:181], v[42:45]
	v_mfma_f32_16x16x32_bf16 v[34:37], v[138:141], v[186:189], v[34:37]
	v_mfma_f32_16x16x32_bf16 v[26:29], v[146:149], v[186:189], v[26:29]
	v_mfma_f32_16x16x32_bf16 v[18:21], v[138:141], v[194:197], v[18:21]
	v_mfma_f32_16x16x32_bf16 v[10:13], v[146:149], v[194:197], v[10:13]
	v_mfma_f32_16x16x32_bf16 v[62:65], v[150:153], v[166:169], v[62:65]
	v_mfma_f32_16x16x32_bf16 v[54:57], v[158:161], v[166:169], v[54:57]
	v_mfma_f32_16x16x32_bf16 v[46:49], v[150:153], v[174:177], v[46:49]
	v_mfma_f32_16x16x32_bf16 v[38:41], v[158:161], v[174:177], v[38:41]
	v_mfma_f32_16x16x32_bf16 v[30:33], v[150:153], v[182:185], v[30:33]
	v_mfma_f32_16x16x32_bf16 v[22:25], v[158:161], v[182:185], v[22:25]
	v_mfma_f32_16x16x32_bf16 v[14:17], v[150:153], v[190:193], v[14:17]
	v_mfma_f32_16x16x32_bf16 v[6:9], v[158:161], v[190:193], v[6:9]
	v_mfma_f32_16x16x32_bf16 v[62:65], v[154:157], v[170:173], v[62:65]
	v_mfma_f32_16x16x32_bf16 v[54:57], v[162:165], v[170:173], v[54:57]
	v_mfma_f32_16x16x32_bf16 v[46:49], v[154:157], v[178:181], v[46:49]
	v_mfma_f32_16x16x32_bf16 v[38:41], v[162:165], v[178:181], v[38:41]
	v_mfma_f32_16x16x32_bf16 v[30:33], v[154:157], v[186:189], v[30:33]
	v_mfma_f32_16x16x32_bf16 v[22:25], v[162:165], v[186:189], v[22:25]
	v_mfma_f32_16x16x32_bf16 v[14:17], v[154:157], v[194:197], v[14:17]
	v_mfma_f32_16x16x32_bf16 v[6:9], v[162:165], v[194:197], v[6:9]
	s_barrier
.Lpeel8_p3:
	ds_read_b128 v[166:169], v220 offset:32768
	ds_read_b128 v[170:173], v220 offset:33792
	ds_read_b128 v[174:177], v220 offset:34816
	ds_read_b128 v[178:181], v220 offset:35840
	ds_read_b128 v[182:185], v220 offset:36864
	ds_read_b128 v[186:189], v220 offset:37888
	ds_read_b128 v[190:193], v220 offset:38912
	ds_read_b128 v[194:197], v220 offset:39936
	v_add_u32_e32 v134, 0x18000, v217
	v_add_u32_e32 v146, 0x1c000, v217
	ds_read_b128 v[150:153], v134
	ds_read_b128 v[154:157], v134 offset:1024
	ds_read_b128 v[158:161], v134 offset:2048
	ds_read_b128 v[162:165], v134 offset:3072
	ds_read_b128 v[134:137], v146
	ds_read_b128 v[138:141], v146 offset:1024
	ds_read_b128 v[142:145], v146 offset:2048
	ds_read_b128 v[146:149], v146 offset:3072
	s_add_i32 s62, 0, 0x18000
	s_add_i32 s63, 0, 0x1c000
	s_add_u32 s48, s48, 0x40000
	s_addc_u32 s49, s49, 0
	s_mov_b32 m0, s42
	s_nop 0
	global_load_lds_dwordx4 v204, s[48:49]
	s_mov_b32 m0, s43
	s_nop 0
	global_load_lds_dwordx4 v200, s[48:49]
	s_waitcnt vmcnt(8) lgkmcnt(0)
	s_barrier
	v_mfma_f32_16x16x32_bf16 v[130:133], v[150:153], v[166:169], v[130:133]
	v_mfma_f32_16x16x32_bf16 v[122:125], v[158:161], v[166:169], v[122:125]
	v_mfma_f32_16x16x32_bf16 v[114:117], v[150:153], v[174:177], v[114:117]
	v_mfma_f32_16x16x32_bf16 v[106:109], v[158:161], v[174:177], v[106:109]
	v_mfma_f32_16x16x32_bf16 v[98:101], v[150:153], v[182:185], v[98:101]
	v_mfma_f32_16x16x32_bf16 v[90:93], v[158:161], v[182:185], v[90:93]
	v_mfma_f32_16x16x32_bf16 v[82:85], v[150:153], v[190:193], v[82:85]
	v_mfma_f32_16x16x32_bf16 v[74:77], v[158:161], v[190:193], v[74:77]
	v_mfma_f32_16x16x32_bf16 v[130:133], v[154:157], v[170:173], v[130:133]
	v_mfma_f32_16x16x32_bf16 v[122:125], v[162:165], v[170:173], v[122:125]
	v_mfma_f32_16x16x32_bf16 v[114:117], v[154:157], v[178:181], v[114:117]
	v_mfma_f32_16x16x32_bf16 v[106:109], v[162:165], v[178:181], v[106:109]
	v_mfma_f32_16x16x32_bf16 v[98:101], v[154:157], v[186:189], v[98:101]
	v_mfma_f32_16x16x32_bf16 v[90:93], v[162:165], v[186:189], v[90:93]
	v_mfma_f32_16x16x32_bf16 v[82:85], v[154:157], v[194:197], v[82:85]
	v_mfma_f32_16x16x32_bf16 v[74:77], v[162:165], v[194:197], v[74:77]
	v_mfma_f32_16x16x32_bf16 v[126:129], v[134:137], v[166:169], v[126:129]
	v_mfma_f32_16x16x32_bf16 v[118:121], v[142:145], v[166:169], v[118:121]
	v_mfma_f32_16x16x32_bf16 v[110:113], v[134:137], v[174:177], v[110:113]
	v_mfma_f32_16x16x32_bf16 v[102:105], v[142:145], v[174:177], v[102:105]
	v_mfma_f32_16x16x32_bf16 v[94:97], v[134:137], v[182:185], v[94:97]
	v_mfma_f32_16x16x32_bf16 v[86:89], v[142:145], v[182:185], v[86:89]
	v_mfma_f32_16x16x32_bf16 v[78:81], v[134:137], v[190:193], v[78:81]
	v_mfma_f32_16x16x32_bf16 v[70:73], v[142:145], v[190:193], v[70:73]
	v_mfma_f32_16x16x32_bf16 v[126:129], v[138:141], v[170:173], v[126:129]
	v_mfma_f32_16x16x32_bf16 v[118:121], v[146:149], v[170:173], v[118:121]
	v_mfma_f32_16x16x32_bf16 v[110:113], v[138:141], v[178:181], v[110:113]
	v_mfma_f32_16x16x32_bf16 v[102:105], v[146:149], v[178:181], v[102:105]
	v_mfma_f32_16x16x32_bf16 v[94:97], v[138:141], v[186:189], v[94:97]
	v_mfma_f32_16x16x32_bf16 v[86:89], v[146:149], v[186:189], v[86:89]
	v_mfma_f32_16x16x32_bf16 v[78:81], v[138:141], v[194:197], v[78:81]
	v_mfma_f32_16x16x32_bf16 v[70:73], v[146:149], v[194:197], v[70:73]
	s_barrier
	ds_read_b128 v[190:193], v220 offset:49152
	ds_read_b128 v[194:197], v220 offset:50176
	ds_read_b128 v[182:185], v220 offset:51200
	ds_read_b128 v[186:189], v220 offset:52224
	ds_read_b128 v[174:177], v220 offset:53248
	ds_read_b128 v[178:181], v220 offset:54272
	ds_read_b128 v[166:169], v220 offset:55296
	ds_read_b128 v[170:173], v220 offset:56320
	s_add_i32 s48, s62, s12
	s_mov_b32 m0, s48
	s_nop 0
	global_load_lds_dwordx4 v202, s[98:99]
	s_add_i32 m0, s48, 0x2000
	s_add_u32 s46, s46, 0x40080
	s_addc_u32 s47, s47, 0
	s_add_i32 s48, s63, s12
	global_load_lds_dwordx4 v198, s[98:99]
	s_mov_b32 m0, s48
	s_andn2_b64 vcc, exec, s[30:31]
	global_load_lds_dwordx4 v202, s[46:47]
	s_add_i32 m0, s48, 0x2000
	s_nop 0
	global_load_lds_dwordx4 v198, s[46:47]
	s_mov_b32 m0, s51
	s_nop 0
	global_load_lds_dwordx4 v204, s[100:101]
	s_mov_b32 m0, s52
	s_nop 0
	global_load_lds_dwordx4 v200, s[100:101]
	s_waitcnt vmcnt(8)
	s_cbranch_vccnz .LBB0_1765
	s_and_saveexec_b64 s[30:31], s[4:5]
	s_cbranch_execz .LBB0_1764
	v_mov_b32_e32 v222, v3
	v_mov_b32_e32 v223, v4
	v_mov_b32_e32 v224, v2
	v_mov_b32_e32 v225, v5
	v_pk_add_f32 v[222:223], v[222:223], v[224:225]
	s_nop 0
	v_add_f32_e32 v222, v222, v223
	v_fmamk_f32 v222, v222, 0x3a800000, v221
	ds_write_b32 v219, v222
	s_branch .LBB0_1764

.LBB0_2024:
	ds_read_b128 v[36:39], v203
	ds_read_b128 v[44:47], v203 offset:1024
	ds_read_b128 v[48:51], v203 offset:2048
	ds_read_b128 v[56:59], v203 offset:3072
	ds_read_b128 v[144:147], v207
	ds_read_b128 v[148:151], v207 offset:1024
	ds_read_b128 v[152:155], v207 offset:2048
	ds_read_b128 v[156:159], v207 offset:3072
	s_add_i32 s46, s46, 1
	s_mul_i32 s0, s46, s54
	s_mul_hi_u32 s1, s46, s3
	s_add_i32 s1, s1, s0
	s_mul_i32 s0, s46, s3
	s_add_u32 s24, s0, s94
	s_addc_u32 s25, s1, s33
	v_mov_b64_e32 v[0:1], 0xff
	v_cmp_gt_i64_e64 s[0:1], s[24:25], v[0:1]
	s_and_b64 vcc, exec, s[0:1]
	s_cbranch_vccnz .LBB0_2030
	s_ashr_i32 s14, s24, 31
	s_lshr_b32 s14, s14, 29
	s_add_i32 s14, s24, s14
	s_and_b32 s15, s14, -8
	s_sub_i32 s15, s24, s15
	s_cmp_gt_i32 s15, -1
	s_mov_b64 s[20:21], -1
	s_cbranch_scc0 .LBB0_2027
	s_lshl_b32 s22, s15, 5
	s_mov_b64 s[20:21], 0

.LBB0_2030:
	s_ashr_i32 s23, s22, 31
	s_lshl_b64 s[14:15], s[22:23], 19
	v_cmp_lt_i64_e32 vcc, s[24:25], v[252:253]
	s_add_u32 s24, s68, s14
	s_addc_u32 s25, s69, s15
	s_and_b64 s[14:15], vcc, exec
	s_cselect_b32 s14, s25, s31
	s_cselect_b32 s15, s24, s30
	s_ashr_i32 s21, s20, 31
	s_lshl_b64 s[26:27], s[20:21], 19
	s_add_u32 s26, s40, s26
	s_addc_u32 s27, s41, s27
	s_and_b64 s[38:39], vcc, exec
	s_cselect_b32 s21, s27, s35
	s_cselect_b32 s23, s26, s34
	s_add_u32 s30, s30, 0x40080
	s_addc_u32 s31, s31, 0
	s_add_u32 s61, s34, 0x100
	s_addc_u32 s62, s35, 0
	s_mov_b32 s63, -2
	s_add_u32 s34, s30, 0xfffc0080
	s_addc_u32 s35, s31, -1
	s_cmp_eq_u32 s63, 12
	s_cselect_b32 s39, s14, s35
	s_cselect_b32 s38, s15, s34
	s_cselect_b32 s35, s21, s62
	s_cselect_b32 s34, s23, s61
	s_add_i32 m0, s29, 0xc000
	ds_read_b128 v[172:175], v209
	ds_read_b128 v[176:179], v209 offset:1024
	ds_read_b128 v[180:183], v209 offset:2048
	ds_read_b128 v[184:187], v209 offset:3072
	ds_read_b128 v[188:191], v209 offset:4096
	ds_read_b128 v[192:195], v209 offset:5120
	ds_read_b128 v[196:199], v209 offset:6144
	ds_read_b128 v[214:217], v209 offset:7168
	global_load_lds_dwordx4 v168, s[30:31]
	s_add_i32 m0, s29, 0xe000
	s_nop 0
	global_load_lds_dwordx4 v170, s[30:31]
	s_waitcnt vmcnt(8) lgkmcnt(0)
	s_barrier
	v_mfma_f32_16x16x32_bf16 v[140:143], v[36:39], v[172:175], 0
	v_mfma_f32_16x16x32_bf16 v[136:139], v[48:51], v[172:175], 0
	v_mfma_f32_16x16x32_bf16 v[124:127], v[36:39], v[180:183], 0
	v_mfma_f32_16x16x32_bf16 v[120:123], v[48:51], v[180:183], 0
	v_mfma_f32_16x16x32_bf16 v[108:111], v[36:39], v[188:191], 0
	v_mfma_f32_16x16x32_bf16 v[104:107], v[48:51], v[188:191], 0
	v_mfma_f32_16x16x32_bf16 v[92:95], v[36:39], v[196:199], 0
	v_mfma_f32_16x16x32_bf16 v[88:91], v[48:51], v[196:199], 0
	v_mfma_f32_16x16x32_bf16 v[140:143], v[44:47], v[176:179], v[140:143]
	v_mfma_f32_16x16x32_bf16 v[136:139], v[56:59], v[176:179], v[136:139]
	v_mfma_f32_16x16x32_bf16 v[124:127], v[44:47], v[184:187], v[124:127]
	v_mfma_f32_16x16x32_bf16 v[120:123], v[56:59], v[184:187], v[120:123]
	v_mfma_f32_16x16x32_bf16 v[108:111], v[44:47], v[192:195], v[108:111]
	v_mfma_f32_16x16x32_bf16 v[104:107], v[56:59], v[192:195], v[104:107]
	v_mfma_f32_16x16x32_bf16 v[92:95], v[44:47], v[214:217], v[92:95]
	v_mfma_f32_16x16x32_bf16 v[88:91], v[56:59], v[214:217], v[88:91]
	v_mfma_f32_16x16x32_bf16 v[132:135], v[144:147], v[172:175], 0
	v_mfma_f32_16x16x32_bf16 v[128:131], v[152:155], v[172:175], 0
	v_mfma_f32_16x16x32_bf16 v[116:119], v[144:147], v[180:183], 0
	v_mfma_f32_16x16x32_bf16 v[112:115], v[152:155], v[180:183], 0
	v_mfma_f32_16x16x32_bf16 v[100:103], v[144:147], v[188:191], 0
	v_mfma_f32_16x16x32_bf16 v[96:99], v[152:155], v[188:191], 0
	v_mfma_f32_16x16x32_bf16 v[84:87], v[144:147], v[196:199], 0
	v_mfma_f32_16x16x32_bf16 v[80:83], v[152:155], v[196:199], 0
	v_mfma_f32_16x16x32_bf16 v[132:135], v[148:151], v[176:179], v[132:135]
	v_mfma_f32_16x16x32_bf16 v[128:131], v[156:159], v[176:179], v[128:131]
	v_mfma_f32_16x16x32_bf16 v[116:119], v[148:151], v[184:187], v[116:119]
	v_mfma_f32_16x16x32_bf16 v[112:115], v[156:159], v[184:187], v[112:115]
	v_mfma_f32_16x16x32_bf16 v[100:103], v[148:151], v[192:195], v[100:103]
	v_mfma_f32_16x16x32_bf16 v[96:99], v[156:159], v[192:195], v[96:99]
	v_mfma_f32_16x16x32_bf16 v[84:87], v[148:151], v[214:217], v[84:87]
	v_mfma_f32_16x16x32_bf16 v[80:83], v[156:159], v[214:217], v[80:83]
	s_barrier
	s_add_i32 s64, s55, s42
	s_add_u32 s98, s34, s16
	s_addc_u32 s99, s35, s17
	s_mov_b32 m0, s64
	ds_read_b128 v[172:175], v209 offset:16384
	ds_read_b128 v[176:179], v209 offset:17408
	ds_read_b128 v[180:183], v209 offset:18432
	ds_read_b128 v[184:187], v209 offset:19456
	ds_read_b128 v[188:191], v209 offset:20480
	ds_read_b128 v[192:195], v209 offset:21504
	ds_read_b128 v[196:199], v209 offset:22528
	ds_read_b128 v[214:217], v209 offset:23552
	global_load_lds_dwordx4 v162, s[34:35]
	s_add_i32 m0, s64, 0x2000
	s_add_u32 s64, s34, 0x40000
	s_addc_u32 s65, s35, 0
	s_add_i32 s66, s56, s42
	global_load_lds_dwordx4 v166, s[34:35]
	s_mov_b32 m0, s66
	s_nop 0
	global_load_lds_dwordx4 v162, s[64:65]
	s_add_i32 m0, s66, 0x2000
	s_nop 0
	global_load_lds_dwordx4 v166, s[64:65]
	s_add_u32 s100, s38, s16
	s_addc_u32 s101, s39, s17
	s_mov_b32 m0, s29
	s_nop 0
	global_load_lds_dwordx4 v160, s[38:39]
	s_mov_b32 m0, s43
	s_nop 0
	global_load_lds_dwordx4 v164, s[38:39]
	s_waitcnt vmcnt(8) lgkmcnt(0)
	s_barrier
	v_mfma_f32_16x16x32_bf16 v[76:79], v[36:39], v[172:175], 0
	v_mfma_f32_16x16x32_bf16 v[72:75], v[48:51], v[172:175], 0
	v_mfma_f32_16x16x32_bf16 v[60:63], v[36:39], v[180:183], 0
	v_mfma_f32_16x16x32_bf16 v[52:55], v[48:51], v[180:183], 0
	v_mfma_f32_16x16x32_bf16 v[28:31], v[36:39], v[188:191], 0
	v_mfma_f32_16x16x32_bf16 v[24:27], v[48:51], v[188:191], 0
	v_mfma_f32_16x16x32_bf16 v[12:15], v[36:39], v[196:199], 0
	v_mfma_f32_16x16x32_bf16 v[8:11], v[48:51], v[196:199], 0
	v_mfma_f32_16x16x32_bf16 v[76:79], v[44:47], v[176:179], v[76:79]
	v_mfma_f32_16x16x32_bf16 v[72:75], v[56:59], v[176:179], v[72:75]
	v_mfma_f32_16x16x32_bf16 v[60:63], v[44:47], v[184:187], v[60:63]
	v_mfma_f32_16x16x32_bf16 v[52:55], v[56:59], v[184:187], v[52:55]
	v_mfma_f32_16x16x32_bf16 v[28:31], v[44:47], v[192:195], v[28:31]
	v_mfma_f32_16x16x32_bf16 v[24:27], v[56:59], v[192:195], v[24:27]
	v_mfma_f32_16x16x32_bf16 v[12:15], v[44:47], v[214:217], v[12:15]
	v_mfma_f32_16x16x32_bf16 v[8:11], v[56:59], v[214:217], v[8:11]
	v_mfma_f32_16x16x32_bf16 v[40:43], v[144:147], v[180:183], 0
	v_mfma_f32_16x16x32_bf16 v[32:35], v[152:155], v[180:183], 0
	v_mfma_f32_16x16x32_bf16 v[20:23], v[144:147], v[188:191], 0
	v_mfma_f32_16x16x32_bf16 v[16:19], v[152:155], v[188:191], 0
	v_mfma_f32_16x16x32_bf16 v[4:7], v[144:147], v[196:199], 0
	v_mfma_f32_16x16x32_bf16 v[0:3], v[152:155], v[196:199], 0
	v_mfma_f32_16x16x32_bf16 v[36:39], v[144:147], v[172:175], 0
	v_mfma_f32_16x16x32_bf16 v[44:47], v[152:155], v[172:175], 0
	v_mfma_f32_16x16x32_bf16 v[40:43], v[148:151], v[184:187], v[40:43]
	v_mfma_f32_16x16x32_bf16 v[32:35], v[156:159], v[184:187], v[32:35]
	v_mfma_f32_16x16x32_bf16 v[20:23], v[148:151], v[192:195], v[20:23]
	v_mfma_f32_16x16x32_bf16 v[16:19], v[156:159], v[192:195], v[16:19]
	v_mfma_f32_16x16x32_bf16 v[4:7], v[148:151], v[214:217], v[4:7]
	v_mfma_f32_16x16x32_bf16 v[0:3], v[156:159], v[214:217], v[0:3]
	v_mfma_f32_16x16x32_bf16 v[36:39], v[148:151], v[176:179], v[36:39]
	v_mfma_f32_16x16x32_bf16 v[44:47], v[156:159], v[176:179], v[44:47]
	s_barrier
	s_branch .Lpeel10_p3
